# P11 tile boundary: drop the compiler vmcnt(0) that made the silu epilogue wait for the just-issued prestage DMA; PRE prologue waits only for the DMA (vmcnt 16/22)
# speedup vs baseline: 1.0049x; 1.0049x over previous
.LBB0_1307:
	v_mov_b32_e32 v150, v124
	v_mov_b32_e32 v151, v116
	v_pk_mul_f32 v[150:151], v[150:151], v[128:129] op_sel_hi:[1,0]
	v_mov_b32_e32 v152, v120
	v_mul_f32_e32 v116, 0xbfb8aa3b, v151
	v_exp_f32_e32 v116, v116
	v_mov_b32_e32 v153, v112
	v_pk_mul_f32 v[152:153], v[152:153], v[128:129] op_sel_hi:[1,0]
	s_lshl_b32 s20, s20, 7
	v_mul_f32_e32 v112, 0xbfb8aa3b, v153
	v_exp_f32_e32 v112, v112
	v_add_f32_e32 v116, 1.0, v116
	v_rcp_f32_e32 v116, v116
	s_ashr_i32 s21, s20, 31
	v_add_f32_e32 v112, 1.0, v112
	v_rcp_f32_e32 v112, v112
	v_mul_f32_e32 v116, v151, v116
	v_mul_f32_e32 v124, v150, v116
	v_mov_b32_e32 v116, v125
	v_pk_mul_f32 v[116:117], v[116:117], v[128:129] op_sel_hi:[1,0]
	v_mul_f32_e32 v120, v153, v112
	v_mul_f32_e32 v112, 0xbfb8aa3b, v117
	v_exp_f32_e32 v125, v112
	v_mov_b32_e32 v112, v121
	v_pk_mul_f32 v[112:113], v[112:113], v[128:129] op_sel_hi:[1,0]
	v_mul_f32_e32 v150, v152, v120
	v_mul_f32_e32 v121, 0xbfb8aa3b, v113
	v_exp_f32_e32 v121, v121
	v_add_f32_e32 v120, 1.0, v125
	v_rcp_f32_e32 v125, v120
	s_lshl_b64 s[20:21], s[20:21], 1
	v_add_f32_e32 v120, 1.0, v121
	v_rcp_f32_e32 v151, v120
	v_mov_b32_e32 v120, v126
	v_mov_b32_e32 v121, v118
	v_pk_mul_f32 v[120:121], v[120:121], v[128:129] op_sel_hi:[1,0]
	v_mul_f32_e32 v117, v117, v125
	v_mul_f32_e32 v118, 0xbfb8aa3b, v121
	v_exp_f32_e32 v118, v118
	v_mul_f32_e32 v125, v116, v117
	v_mov_b32_e32 v117, v114
	v_mul_f32_e32 v113, v113, v151
	v_add_f32_e32 v116, 1.0, v118
	v_rcp_f32_e32 v118, v116
	v_mov_b32_e32 v116, v122
	v_pk_mul_f32 v[116:117], v[116:117], v[128:129] op_sel_hi:[1,0]
	v_mul_f32_e32 v122, v112, v113
	v_mul_f32_e32 v114, 0xbfb8aa3b, v117
	v_exp_f32_e32 v114, v114
	v_mul_f32_e32 v112, v121, v118
	v_mul_f32_e32 v120, v120, v112
	v_mov_b32_e32 v118, v127
	v_add_f32_e32 v112, 1.0, v114
	v_rcp_f32_e32 v121, v112
	v_pk_mul_f32 v[112:113], v[118:119], v[128:129] op_sel_hi:[1,0]
	v_or_b32_e32 v145, 16, v148
	v_mul_f32_e32 v114, 0xbfb8aa3b, v113
	v_exp_f32_e32 v118, v114
	v_mov_b32_e32 v114, v123
	v_pk_mul_f32 v[114:115], v[114:115], v[128:129] op_sel_hi:[1,0]
	v_mul_f32_e32 v117, v117, v121
	v_mul_f32_e32 v119, 0xbfb8aa3b, v115
	v_exp_f32_e32 v119, v119
	v_add_f32_e32 v118, 1.0, v118
	v_rcp_f32_e32 v118, v118
	v_mul_f32_e32 v121, v116, v117
	v_add_f32_e32 v119, 1.0, v119
	v_rcp_f32_e32 v119, v119
	v_mul_f32_e32 v113, v113, v118
	v_mul_f32_e32 v112, v112, v113
	v_cvt_pk_bf16_f32 v117, v120, v112
	v_mul_f32_e32 v113, v115, v119
	v_mul_f32_e32 v113, v114, v113
	v_cvt_pk_bf16_f32 v119, v121, v113
	v_mov_b64_e32 v[112:113], s[66:67]
	v_mad_i64_i32 v[114:115], s[22:23], v148, s36, v[112:113]
	v_lshl_add_u64 v[114:115], v[114:115], 0, s[20:21]
	v_and_b32_e32 v128, 0xc0, v143
	v_lshl_add_u64 v[120:121], v[114:115], 0, v[128:129]
	v_and_b32_e32 v114, 48, v143
	v_mov_b32_e32 v115, v129
	v_lshl_add_u64 v[120:121], v[120:121], 0, v[114:115]
	v_or_b32_e32 v147, 32, v148
	v_or_b32_e32 v149, 48, v148
	v_add_u32_e32 v141, 0x80, v148
	v_add_u32_e32 v139, 0x90, v148
	v_add_u32_e32 v135, 0xa0, v148
	v_add_u32_e32 v131, 0xb0, v148
	v_cvt_pk_bf16_f32 v116, v124, v125
	v_cvt_pk_bf16_f32 v118, v150, v122
	global_store_dwordx4 v[120:121], v[116:119], off
	s_nop 1
	v_mov_b32_e32 v116, v108
	v_mov_b32_e32 v117, v100
	v_pk_mul_f32 v[116:117], v[116:117], v[146:147] op_sel_hi:[1,0]
	v_mov_b32_e32 v118, v104
	v_mul_f32_e32 v100, 0xbfb8aa3b, v117
	v_exp_f32_e32 v100, v100
	v_mov_b32_e32 v119, v96
	v_pk_mul_f32 v[118:119], v[118:119], v[146:147] op_sel_hi:[1,0]
	v_add_f32_e32 v100, 1.0, v100
	v_mul_f32_e32 v96, 0xbfb8aa3b, v119
	v_exp_f32_e32 v96, v96
	v_rcp_f32_e32 v100, v100
	v_add_f32_e32 v96, 1.0, v96
	v_rcp_f32_e32 v96, v96
	v_mul_f32_e32 v100, v117, v100
	v_mul_f32_e32 v108, v116, v100
	v_mov_b32_e32 v100, v109
	v_pk_mul_f32 v[100:101], v[100:101], v[146:147] op_sel_hi:[1,0]
	v_mul_f32_e32 v104, v119, v96
	v_mul_f32_e32 v96, 0xbfb8aa3b, v101
	v_exp_f32_e32 v109, v96
	v_mov_b32_e32 v96, v105
	v_pk_mul_f32 v[96:97], v[96:97], v[146:147] op_sel_hi:[1,0]
	v_mul_f32_e32 v116, v118, v104
	v_mul_f32_e32 v105, 0xbfb8aa3b, v97
	v_exp_f32_e32 v105, v105
	v_add_f32_e32 v104, 1.0, v109
	v_rcp_f32_e32 v109, v104
	v_add_f32_e32 v104, 1.0, v105
	v_rcp_f32_e32 v117, v104
	v_mov_b32_e32 v104, v110
	v_mov_b32_e32 v105, v102
	v_pk_mul_f32 v[104:105], v[104:105], v[146:147] op_sel_hi:[1,0]
	v_mul_f32_e32 v101, v101, v109
	v_mul_f32_e32 v102, 0xbfb8aa3b, v105
	v_exp_f32_e32 v102, v102
	v_mul_f32_e32 v109, v100, v101
	v_mov_b32_e32 v101, v98
	v_mul_f32_e32 v97, v97, v117
	v_add_f32_e32 v100, 1.0, v102
	v_rcp_f32_e32 v102, v100
	v_mov_b32_e32 v100, v106
	v_pk_mul_f32 v[100:101], v[100:101], v[146:147] op_sel_hi:[1,0]
	v_mul_f32_e32 v106, v96, v97
	v_mul_f32_e32 v98, 0xbfb8aa3b, v101
	v_exp_f32_e32 v98, v98
	v_mul_f32_e32 v96, v105, v102
	v_mul_f32_e32 v104, v104, v96
	v_mov_b32_e32 v102, v111
	v_add_f32_e32 v96, 1.0, v98
	v_rcp_f32_e32 v105, v96
	v_pk_mul_f32 v[96:97], v[102:103], v[146:147] op_sel_hi:[1,0]
	v_mul_f32_e32 v101, v101, v105
	v_mul_f32_e32 v98, 0xbfb8aa3b, v97
	v_exp_f32_e32 v102, v98
	v_mov_b32_e32 v98, v107
	v_pk_mul_f32 v[98:99], v[98:99], v[146:147] op_sel_hi:[1,0]
	v_mul_f32_e32 v100, v100, v101
	v_mul_f32_e32 v103, 0xbfb8aa3b, v99
	v_exp_f32_e32 v103, v103
	v_add_f32_e32 v102, 1.0, v102
	v_rcp_f32_e32 v102, v102
	v_add_f32_e32 v103, 1.0, v103
	v_rcp_f32_e32 v103, v103
	v_mul_f32_e32 v97, v97, v102
	v_mul_f32_e32 v97, v96, v97
	v_cvt_pk_bf16_f32 v97, v104, v97
	v_mul_f32_e32 v96, v99, v103
	v_mul_f32_e32 v99, v98, v96
	v_cvt_pk_bf16_f32 v99, v100, v99
	v_mad_i64_i32 v[100:101], s[22:23], v145, s36, v[112:113]
	v_lshl_add_u64 v[100:101], v[100:101], 0, s[20:21]
	v_lshl_add_u64 v[100:101], v[100:101], 0, v[128:129]
	v_lshl_add_u64 v[100:101], v[100:101], 0, v[114:115]
	v_cvt_pk_bf16_f32 v96, v108, v109
	v_cvt_pk_bf16_f32 v98, v116, v106
	global_store_dwordx4 v[100:101], v[96:99], off
	s_nop 1
	v_mov_b32_e32 v96, v92
	v_mov_b32_e32 v97, v84
	v_pk_mul_f32 v[96:97], v[96:97], v[144:145] op_sel_hi:[1,0]
	v_mov_b32_e32 v98, v88
	v_mul_f32_e32 v84, 0xbfb8aa3b, v97
	v_exp_f32_e32 v84, v84
	v_mov_b32_e32 v99, v80
	v_pk_mul_f32 v[98:99], v[98:99], v[144:145] op_sel_hi:[1,0]
	v_add_f32_e32 v84, 1.0, v84
	v_mul_f32_e32 v80, 0xbfb8aa3b, v99
	v_exp_f32_e32 v80, v80
	v_rcp_f32_e32 v84, v84
	v_add_f32_e32 v80, 1.0, v80
	v_rcp_f32_e32 v80, v80
	v_mul_f32_e32 v84, v97, v84
	v_mul_f32_e32 v92, v96, v84
	v_mov_b32_e32 v84, v93
	v_pk_mul_f32 v[84:85], v[84:85], v[144:145] op_sel_hi:[1,0]
	v_mul_f32_e32 v88, v99, v80
	v_mul_f32_e32 v80, 0xbfb8aa3b, v85
	v_exp_f32_e32 v93, v80
	v_mov_b32_e32 v80, v89
	v_pk_mul_f32 v[80:81], v[80:81], v[144:145] op_sel_hi:[1,0]
	v_mul_f32_e32 v96, v98, v88
	v_mul_f32_e32 v89, 0xbfb8aa3b, v81
	v_exp_f32_e32 v89, v89
	v_add_f32_e32 v88, 1.0, v93
	v_rcp_f32_e32 v93, v88
	v_add_f32_e32 v88, 1.0, v89
	v_rcp_f32_e32 v97, v88
	v_mov_b32_e32 v88, v94
	v_mov_b32_e32 v89, v86
	v_pk_mul_f32 v[88:89], v[88:89], v[144:145] op_sel_hi:[1,0]
	v_mul_f32_e32 v85, v85, v93
	v_mul_f32_e32 v86, 0xbfb8aa3b, v89
	v_exp_f32_e32 v86, v86
	v_mul_f32_e32 v93, v84, v85
	v_mov_b32_e32 v85, v82
	v_mul_f32_e32 v81, v81, v97
	v_add_f32_e32 v84, 1.0, v86
	v_rcp_f32_e32 v86, v84
	v_mov_b32_e32 v84, v90
	v_pk_mul_f32 v[84:85], v[84:85], v[144:145] op_sel_hi:[1,0]
	v_mul_f32_e32 v90, v80, v81
	v_mul_f32_e32 v82, 0xbfb8aa3b, v85
	v_exp_f32_e32 v82, v82
	v_mul_f32_e32 v80, v89, v86
	v_mul_f32_e32 v88, v88, v80
	v_mov_b32_e32 v86, v95
	v_add_f32_e32 v80, 1.0, v82
	v_rcp_f32_e32 v89, v80
	v_pk_mul_f32 v[80:81], v[86:87], v[144:145] op_sel_hi:[1,0]
	v_mul_f32_e32 v85, v85, v89
	v_mul_f32_e32 v82, 0xbfb8aa3b, v81
	v_exp_f32_e32 v86, v82
	v_mov_b32_e32 v82, v91
	v_pk_mul_f32 v[82:83], v[82:83], v[144:145] op_sel_hi:[1,0]
	v_mul_f32_e32 v84, v84, v85
	v_mul_f32_e32 v87, 0xbfb8aa3b, v83
	v_exp_f32_e32 v87, v87
	v_add_f32_e32 v86, 1.0, v86
	v_rcp_f32_e32 v86, v86
	v_add_f32_e32 v87, 1.0, v87
	v_rcp_f32_e32 v87, v87
	v_mul_f32_e32 v81, v81, v86
	v_mul_f32_e32 v81, v80, v81
	v_cvt_pk_bf16_f32 v81, v88, v81
	v_mul_f32_e32 v80, v83, v87
	v_mul_f32_e32 v83, v82, v80
	v_cvt_pk_bf16_f32 v83, v84, v83
	v_mad_i64_i32 v[84:85], s[22:23], v147, s36, v[112:113]
	v_lshl_add_u64 v[84:85], v[84:85], 0, s[20:21]
	v_lshl_add_u64 v[84:85], v[84:85], 0, v[128:129]
	v_lshl_add_u64 v[84:85], v[84:85], 0, v[114:115]
	v_cvt_pk_bf16_f32 v80, v92, v93
	v_cvt_pk_bf16_f32 v82, v96, v90
	global_store_dwordx4 v[84:85], v[80:83], off
	s_nop 1
	v_mov_b32_e32 v80, v76
	v_mov_b32_e32 v81, v68
	v_pk_mul_f32 v[80:81], v[80:81], v[142:143] op_sel_hi:[1,0]
	v_mov_b32_e32 v82, v72
	v_mul_f32_e32 v68, 0xbfb8aa3b, v81
	v_exp_f32_e32 v68, v68
	v_mov_b32_e32 v83, v64
	v_pk_mul_f32 v[82:83], v[82:83], v[142:143] op_sel_hi:[1,0]
	v_add_f32_e32 v68, 1.0, v68
	v_mul_f32_e32 v64, 0xbfb8aa3b, v83
	v_exp_f32_e32 v64, v64
	v_rcp_f32_e32 v68, v68
	v_add_f32_e32 v64, 1.0, v64
	v_rcp_f32_e32 v64, v64
	v_mul_f32_e32 v68, v81, v68
	v_mul_f32_e32 v76, v80, v68
	v_mov_b32_e32 v68, v77
	v_pk_mul_f32 v[68:69], v[68:69], v[142:143] op_sel_hi:[1,0]
	v_mul_f32_e32 v72, v83, v64
	v_mul_f32_e32 v64, 0xbfb8aa3b, v69
	v_exp_f32_e32 v77, v64
	v_mov_b32_e32 v64, v73
	v_pk_mul_f32 v[64:65], v[64:65], v[142:143] op_sel_hi:[1,0]
	v_mul_f32_e32 v80, v82, v72
	v_mul_f32_e32 v73, 0xbfb8aa3b, v65
	v_exp_f32_e32 v73, v73
	v_add_f32_e32 v72, 1.0, v77
	v_rcp_f32_e32 v77, v72
	v_add_f32_e32 v72, 1.0, v73
	v_rcp_f32_e32 v81, v72
	v_mov_b32_e32 v72, v78
	v_mov_b32_e32 v73, v70
	v_pk_mul_f32 v[72:73], v[72:73], v[142:143] op_sel_hi:[1,0]
	v_mul_f32_e32 v69, v69, v77
	v_mul_f32_e32 v70, 0xbfb8aa3b, v73
	v_exp_f32_e32 v70, v70
	v_mul_f32_e32 v77, v68, v69
	v_mov_b32_e32 v69, v66
	v_mul_f32_e32 v65, v65, v81
	v_add_f32_e32 v68, 1.0, v70
	v_rcp_f32_e32 v70, v68
	v_mov_b32_e32 v68, v74
	v_pk_mul_f32 v[68:69], v[68:69], v[142:143] op_sel_hi:[1,0]
	v_mul_f32_e32 v74, v64, v65
	v_mul_f32_e32 v66, 0xbfb8aa3b, v69
	v_exp_f32_e32 v66, v66
	v_mul_f32_e32 v64, v73, v70
	v_mul_f32_e32 v72, v72, v64
	v_mov_b32_e32 v70, v79
	v_add_f32_e32 v64, 1.0, v66
	v_rcp_f32_e32 v73, v64
	v_pk_mul_f32 v[64:65], v[70:71], v[142:143] op_sel_hi:[1,0]
	v_mul_f32_e32 v69, v69, v73
	v_mul_f32_e32 v66, 0xbfb8aa3b, v65
	v_exp_f32_e32 v70, v66
	v_mov_b32_e32 v66, v75
	v_pk_mul_f32 v[66:67], v[66:67], v[142:143] op_sel_hi:[1,0]
	v_mul_f32_e32 v68, v68, v69
	v_mul_f32_e32 v71, 0xbfb8aa3b, v67
	v_exp_f32_e32 v71, v71
	v_add_f32_e32 v70, 1.0, v70
	v_rcp_f32_e32 v70, v70
	v_add_f32_e32 v71, 1.0, v71
	v_rcp_f32_e32 v71, v71
	v_mul_f32_e32 v65, v65, v70
	v_mul_f32_e32 v65, v64, v65
	v_cvt_pk_bf16_f32 v65, v72, v65
	v_mul_f32_e32 v64, v67, v71
	v_mul_f32_e32 v67, v66, v64
	v_cvt_pk_bf16_f32 v67, v68, v67
	v_mad_i64_i32 v[68:69], s[22:23], v149, s36, v[112:113]
	v_lshl_add_u64 v[68:69], v[68:69], 0, s[20:21]
	v_lshl_add_u64 v[68:69], v[68:69], 0, v[128:129]
	v_lshl_add_u64 v[68:69], v[68:69], 0, v[114:115]
	v_cvt_pk_bf16_f32 v64, v76, v77
	v_cvt_pk_bf16_f32 v66, v80, v74
	global_store_dwordx4 v[68:69], v[64:67], off
	s_nop 1
	v_mov_b32_e32 v64, v60
	v_mov_b32_e32 v65, v52
	v_pk_mul_f32 v[64:65], v[64:65], v[140:141] op_sel_hi:[1,0]
	v_mov_b32_e32 v66, v56
	v_mul_f32_e32 v52, 0xbfb8aa3b, v65
	v_exp_f32_e32 v52, v52
	v_mov_b32_e32 v67, v48
	v_pk_mul_f32 v[66:67], v[66:67], v[140:141] op_sel_hi:[1,0]
	v_add_f32_e32 v52, 1.0, v52
	v_mul_f32_e32 v48, 0xbfb8aa3b, v67
	v_exp_f32_e32 v48, v48
	v_rcp_f32_e32 v52, v52
	v_add_f32_e32 v48, 1.0, v48
	v_rcp_f32_e32 v48, v48
	v_mul_f32_e32 v52, v65, v52
	v_mul_f32_e32 v60, v64, v52
	v_mov_b32_e32 v52, v61
	v_pk_mul_f32 v[52:53], v[52:53], v[140:141] op_sel_hi:[1,0]
	v_mul_f32_e32 v56, v67, v48
	v_mul_f32_e32 v48, 0xbfb8aa3b, v53
	v_exp_f32_e32 v61, v48
	v_mov_b32_e32 v48, v57
	v_pk_mul_f32 v[48:49], v[48:49], v[140:141] op_sel_hi:[1,0]
	v_mul_f32_e32 v64, v66, v56
	v_mul_f32_e32 v57, 0xbfb8aa3b, v49
	v_exp_f32_e32 v57, v57
	v_add_f32_e32 v56, 1.0, v61
	v_rcp_f32_e32 v61, v56
	v_add_f32_e32 v56, 1.0, v57
	v_rcp_f32_e32 v65, v56
	v_mov_b32_e32 v56, v62
	v_mov_b32_e32 v57, v54
	v_pk_mul_f32 v[56:57], v[56:57], v[140:141] op_sel_hi:[1,0]
	v_mul_f32_e32 v53, v53, v61
	v_mul_f32_e32 v54, 0xbfb8aa3b, v57
	v_exp_f32_e32 v54, v54
	v_mul_f32_e32 v61, v52, v53
	v_mov_b32_e32 v53, v50
	v_mul_f32_e32 v49, v49, v65
	v_add_f32_e32 v52, 1.0, v54
	v_rcp_f32_e32 v54, v52
	v_mov_b32_e32 v52, v58
	v_pk_mul_f32 v[52:53], v[52:53], v[140:141] op_sel_hi:[1,0]
	v_mul_f32_e32 v58, v48, v49
	v_mul_f32_e32 v50, 0xbfb8aa3b, v53
	v_exp_f32_e32 v50, v50
	v_mul_f32_e32 v48, v57, v54
	v_mul_f32_e32 v56, v56, v48
	v_mov_b32_e32 v54, v63
	v_add_f32_e32 v48, 1.0, v50
	v_rcp_f32_e32 v57, v48
	v_pk_mul_f32 v[48:49], v[54:55], v[140:141] op_sel_hi:[1,0]
	v_mul_f32_e32 v53, v53, v57
	v_mul_f32_e32 v50, 0xbfb8aa3b, v49
	v_exp_f32_e32 v54, v50
	v_mov_b32_e32 v50, v59
	v_pk_mul_f32 v[50:51], v[50:51], v[140:141] op_sel_hi:[1,0]
	v_mul_f32_e32 v52, v52, v53
	v_mul_f32_e32 v55, 0xbfb8aa3b, v51
	v_exp_f32_e32 v55, v55
	v_add_f32_e32 v54, 1.0, v54
	v_rcp_f32_e32 v54, v54
	v_add_f32_e32 v55, 1.0, v55
	v_rcp_f32_e32 v55, v55
	v_mul_f32_e32 v49, v49, v54
	v_mul_f32_e32 v49, v48, v49
	v_cvt_pk_bf16_f32 v49, v56, v49
	v_mul_f32_e32 v48, v51, v55
	v_mul_f32_e32 v51, v50, v48
	v_cvt_pk_bf16_f32 v51, v52, v51
	v_mad_i64_i32 v[52:53], s[22:23], v141, s36, v[112:113]
	v_lshl_add_u64 v[52:53], v[52:53], 0, s[20:21]
	v_lshl_add_u64 v[52:53], v[52:53], 0, v[128:129]
	v_lshl_add_u64 v[52:53], v[52:53], 0, v[114:115]
	v_cvt_pk_bf16_f32 v48, v60, v61
	v_cvt_pk_bf16_f32 v50, v64, v58
	global_store_dwordx4 v[52:53], v[48:51], off
	s_nop 1
	v_mov_b32_e32 v48, v44
	v_mov_b32_e32 v49, v36
	v_pk_mul_f32 v[48:49], v[48:49], v[138:139] op_sel_hi:[1,0]
	v_mov_b32_e32 v50, v40
	v_mul_f32_e32 v36, 0xbfb8aa3b, v49
	v_exp_f32_e32 v36, v36
	v_mov_b32_e32 v51, v32
	v_pk_mul_f32 v[50:51], v[50:51], v[138:139] op_sel_hi:[1,0]
	v_add_f32_e32 v36, 1.0, v36
	v_mul_f32_e32 v32, 0xbfb8aa3b, v51
	v_exp_f32_e32 v32, v32
	v_rcp_f32_e32 v36, v36
	v_add_f32_e32 v32, 1.0, v32
	v_rcp_f32_e32 v32, v32
	v_mul_f32_e32 v36, v49, v36
	v_mul_f32_e32 v44, v48, v36
	v_mov_b32_e32 v36, v45
	v_pk_mul_f32 v[36:37], v[36:37], v[138:139] op_sel_hi:[1,0]
	v_mul_f32_e32 v40, v51, v32
	v_mul_f32_e32 v32, 0xbfb8aa3b, v37
	v_exp_f32_e32 v45, v32
	v_mov_b32_e32 v32, v41
	v_pk_mul_f32 v[32:33], v[32:33], v[138:139] op_sel_hi:[1,0]
	v_mul_f32_e32 v48, v50, v40
	v_mul_f32_e32 v41, 0xbfb8aa3b, v33
	v_exp_f32_e32 v41, v41
	v_add_f32_e32 v40, 1.0, v45
	v_rcp_f32_e32 v45, v40
	v_add_f32_e32 v40, 1.0, v41
	v_rcp_f32_e32 v49, v40
	v_mov_b32_e32 v40, v46
	v_mov_b32_e32 v41, v38
	v_pk_mul_f32 v[40:41], v[40:41], v[138:139] op_sel_hi:[1,0]
	v_mul_f32_e32 v37, v37, v45
	v_mul_f32_e32 v38, 0xbfb8aa3b, v41
	v_exp_f32_e32 v38, v38
	v_mul_f32_e32 v45, v36, v37
	v_mov_b32_e32 v37, v34
	v_mul_f32_e32 v33, v33, v49
	v_add_f32_e32 v36, 1.0, v38
	v_rcp_f32_e32 v38, v36
	v_mov_b32_e32 v36, v42
	v_pk_mul_f32 v[36:37], v[36:37], v[138:139] op_sel_hi:[1,0]
	v_mul_f32_e32 v42, v32, v33
	v_mul_f32_e32 v34, 0xbfb8aa3b, v37
	v_exp_f32_e32 v34, v34
	v_mul_f32_e32 v32, v41, v38
	v_mul_f32_e32 v40, v40, v32
	v_mov_b32_e32 v38, v47
	v_add_f32_e32 v32, 1.0, v34
	v_rcp_f32_e32 v41, v32
	v_pk_mul_f32 v[32:33], v[38:39], v[138:139] op_sel_hi:[1,0]
	v_mul_f32_e32 v37, v37, v41
	v_mul_f32_e32 v34, 0xbfb8aa3b, v33
	v_exp_f32_e32 v38, v34
	v_mov_b32_e32 v34, v43
	v_pk_mul_f32 v[34:35], v[34:35], v[138:139] op_sel_hi:[1,0]
	v_mul_f32_e32 v36, v36, v37
	v_mul_f32_e32 v39, 0xbfb8aa3b, v35
	v_exp_f32_e32 v39, v39
	v_add_f32_e32 v38, 1.0, v38
	v_rcp_f32_e32 v38, v38
	v_add_f32_e32 v39, 1.0, v39
	v_rcp_f32_e32 v39, v39
	v_mul_f32_e32 v33, v33, v38
	v_mul_f32_e32 v33, v32, v33
	v_cvt_pk_bf16_f32 v33, v40, v33
	v_mul_f32_e32 v32, v35, v39
	v_mul_f32_e32 v35, v34, v32
	v_cvt_pk_bf16_f32 v35, v36, v35
	v_mad_i64_i32 v[36:37], s[22:23], v139, s36, v[112:113]
	v_lshl_add_u64 v[36:37], v[36:37], 0, s[20:21]
	v_lshl_add_u64 v[36:37], v[36:37], 0, v[128:129]
	v_lshl_add_u64 v[36:37], v[36:37], 0, v[114:115]
	v_cvt_pk_bf16_f32 v32, v44, v45
	v_cvt_pk_bf16_f32 v34, v48, v42
	global_store_dwordx4 v[36:37], v[32:35], off
	s_nop 1
	v_mov_b32_e32 v32, v28
	v_mov_b32_e32 v33, v20
	v_pk_mul_f32 v[32:33], v[32:33], v[134:135] op_sel_hi:[1,0]
	v_mov_b32_e32 v34, v24
	v_mul_f32_e32 v20, 0xbfb8aa3b, v33
	v_exp_f32_e32 v20, v20
	v_mov_b32_e32 v35, v16
	v_pk_mul_f32 v[34:35], v[34:35], v[134:135] op_sel_hi:[1,0]
	v_add_f32_e32 v20, 1.0, v20
	v_mul_f32_e32 v16, 0xbfb8aa3b, v35
	v_exp_f32_e32 v16, v16
	v_rcp_f32_e32 v20, v20
	v_add_f32_e32 v16, 1.0, v16
	v_rcp_f32_e32 v16, v16
	v_mul_f32_e32 v20, v33, v20
	v_mul_f32_e32 v28, v32, v20
	v_mov_b32_e32 v20, v29
	v_pk_mul_f32 v[20:21], v[20:21], v[134:135] op_sel_hi:[1,0]
	v_mul_f32_e32 v24, v35, v16
	v_mul_f32_e32 v16, 0xbfb8aa3b, v21
	v_exp_f32_e32 v29, v16
	v_mov_b32_e32 v16, v25
	v_pk_mul_f32 v[16:17], v[16:17], v[134:135] op_sel_hi:[1,0]
	v_mul_f32_e32 v32, v34, v24
	v_mul_f32_e32 v25, 0xbfb8aa3b, v17
	v_exp_f32_e32 v25, v25
	v_add_f32_e32 v24, 1.0, v29
	v_rcp_f32_e32 v29, v24
	v_add_f32_e32 v24, 1.0, v25
	v_rcp_f32_e32 v33, v24
	v_mov_b32_e32 v24, v30
	v_mov_b32_e32 v25, v22
	v_pk_mul_f32 v[24:25], v[24:25], v[134:135] op_sel_hi:[1,0]
	v_mul_f32_e32 v21, v21, v29
	v_mul_f32_e32 v22, 0xbfb8aa3b, v25
	v_exp_f32_e32 v22, v22
	v_mul_f32_e32 v29, v20, v21
	v_mov_b32_e32 v21, v18
	v_mul_f32_e32 v17, v17, v33
	v_add_f32_e32 v20, 1.0, v22
	v_rcp_f32_e32 v22, v20
	v_mov_b32_e32 v20, v26
	v_pk_mul_f32 v[20:21], v[20:21], v[134:135] op_sel_hi:[1,0]
	v_mul_f32_e32 v26, v16, v17
	v_mul_f32_e32 v18, 0xbfb8aa3b, v21
	v_exp_f32_e32 v18, v18
	v_mul_f32_e32 v16, v25, v22
	v_mul_f32_e32 v24, v24, v16
	v_mov_b32_e32 v22, v31
	v_add_f32_e32 v16, 1.0, v18
	v_rcp_f32_e32 v25, v16
	v_pk_mul_f32 v[16:17], v[22:23], v[134:135] op_sel_hi:[1,0]
	v_mul_f32_e32 v21, v21, v25
	v_mul_f32_e32 v18, 0xbfb8aa3b, v17
	v_exp_f32_e32 v22, v18
	v_mov_b32_e32 v18, v27
	v_pk_mul_f32 v[18:19], v[18:19], v[134:135] op_sel_hi:[1,0]
	v_mul_f32_e32 v20, v20, v21
	v_mul_f32_e32 v23, 0xbfb8aa3b, v19
	v_exp_f32_e32 v23, v23
	v_add_f32_e32 v22, 1.0, v22
	v_rcp_f32_e32 v22, v22
	v_add_f32_e32 v23, 1.0, v23
	v_rcp_f32_e32 v23, v23
	v_mul_f32_e32 v17, v17, v22
	v_mul_f32_e32 v17, v16, v17
	v_cvt_pk_bf16_f32 v17, v24, v17
	v_mul_f32_e32 v16, v19, v23
	v_mul_f32_e32 v19, v18, v16
	v_cvt_pk_bf16_f32 v19, v20, v19
	v_mad_i64_i32 v[20:21], s[22:23], v135, s36, v[112:113]
	v_lshl_add_u64 v[20:21], v[20:21], 0, s[20:21]
	v_lshl_add_u64 v[20:21], v[20:21], 0, v[128:129]
	v_lshl_add_u64 v[20:21], v[20:21], 0, v[114:115]
	v_cvt_pk_bf16_f32 v16, v28, v29
	v_cvt_pk_bf16_f32 v18, v32, v26
	global_store_dwordx4 v[20:21], v[16:19], off
	s_nop 1
	v_mov_b32_e32 v16, v12
	v_mov_b32_e32 v17, v4
	v_pk_mul_f32 v[16:17], v[16:17], v[130:131] op_sel_hi:[1,0]
	v_mov_b32_e32 v18, v8
	v_mul_f32_e32 v4, 0xbfb8aa3b, v17
	v_exp_f32_e32 v4, v4
	v_mov_b32_e32 v19, v0
	v_pk_mul_f32 v[18:19], v[18:19], v[130:131] op_sel_hi:[1,0]
	v_add_f32_e32 v4, 1.0, v4
	v_mul_f32_e32 v0, 0xbfb8aa3b, v19
	v_exp_f32_e32 v0, v0
	v_rcp_f32_e32 v4, v4
	v_add_f32_e32 v0, 1.0, v0
	v_rcp_f32_e32 v0, v0
	v_mul_f32_e32 v4, v17, v4
	v_mul_f32_e32 v12, v16, v4
	v_mov_b32_e32 v4, v13
	v_pk_mul_f32 v[4:5], v[4:5], v[130:131] op_sel_hi:[1,0]
	v_mul_f32_e32 v8, v19, v0
	v_mul_f32_e32 v0, 0xbfb8aa3b, v5
	v_exp_f32_e32 v13, v0
	v_mov_b32_e32 v0, v9
	v_pk_mul_f32 v[0:1], v[0:1], v[130:131] op_sel_hi:[1,0]
	v_mul_f32_e32 v16, v18, v8
	v_mul_f32_e32 v9, 0xbfb8aa3b, v1
	v_exp_f32_e32 v9, v9
	v_add_f32_e32 v8, 1.0, v13
	v_rcp_f32_e32 v13, v8
	v_add_f32_e32 v8, 1.0, v9
	v_rcp_f32_e32 v17, v8
	v_mov_b32_e32 v8, v14
	v_mov_b32_e32 v9, v6
	v_pk_mul_f32 v[8:9], v[8:9], v[130:131] op_sel_hi:[1,0]
	v_mul_f32_e32 v5, v5, v13
	v_mul_f32_e32 v6, 0xbfb8aa3b, v9
	v_exp_f32_e32 v6, v6
	v_mul_f32_e32 v13, v4, v5
	v_mov_b32_e32 v5, v2
	v_mul_f32_e32 v1, v1, v17
	v_add_f32_e32 v4, 1.0, v6
	v_rcp_f32_e32 v6, v4
	v_mov_b32_e32 v4, v10
	v_pk_mul_f32 v[4:5], v[4:5], v[130:131] op_sel_hi:[1,0]
	v_mul_f32_e32 v10, v0, v1
	v_mul_f32_e32 v2, 0xbfb8aa3b, v5
	v_exp_f32_e32 v2, v2
	v_mul_f32_e32 v0, v9, v6
	v_mul_f32_e32 v8, v8, v0
	v_mov_b32_e32 v6, v15
	v_add_f32_e32 v0, 1.0, v2
	v_rcp_f32_e32 v9, v0
	v_pk_mul_f32 v[0:1], v[6:7], v[130:131] op_sel_hi:[1,0]
	v_mul_f32_e32 v5, v5, v9
	v_mul_f32_e32 v2, 0xbfb8aa3b, v1
	v_exp_f32_e32 v6, v2
	v_mov_b32_e32 v2, v11
	v_pk_mul_f32 v[2:3], v[2:3], v[130:131] op_sel_hi:[1,0]
	v_mul_f32_e32 v4, v4, v5
	v_mul_f32_e32 v7, 0xbfb8aa3b, v3
	v_exp_f32_e32 v7, v7
	v_add_f32_e32 v6, 1.0, v6
	v_rcp_f32_e32 v6, v6
	v_add_f32_e32 v7, 1.0, v7
	v_rcp_f32_e32 v7, v7
	v_mul_f32_e32 v1, v1, v6
	v_mul_f32_e32 v1, v0, v1
	v_cvt_pk_bf16_f32 v1, v8, v1
	v_mul_f32_e32 v0, v3, v7
	v_mul_f32_e32 v3, v2, v0
	v_cvt_pk_bf16_f32 v3, v4, v3
	v_mad_i64_i32 v[4:5], s[22:23], v131, s36, v[112:113]
	v_lshl_add_u64 v[4:5], v[4:5], 0, s[20:21]
	v_lshl_add_u64 v[4:5], v[4:5], 0, v[128:129]
	v_lshl_add_u64 v[4:5], v[4:5], 0, v[114:115]
	v_cvt_pk_bf16_f32 v0, v12, v13
	v_cvt_pk_bf16_f32 v2, v16, v10
	global_store_dwordx4 v[4:5], v[0:3], off

.LBB0_1322:
	v_mov_b32_e32 v150, v124
	v_mov_b32_e32 v151, v116
	v_pk_mul_f32 v[150:151], v[150:151], v[128:129] op_sel_hi:[1,0]
	v_mov_b32_e32 v152, v120
	v_mul_f32_e32 v116, 0xbfb8aa3b, v151
	v_exp_f32_e32 v116, v116
	v_mov_b32_e32 v153, v112
	v_pk_mul_f32 v[152:153], v[152:153], v[128:129] op_sel_hi:[1,0]
	s_lshl_b32 s40, s20, 7
	v_mul_f32_e32 v112, 0xbfb8aa3b, v153
	v_exp_f32_e32 v112, v112
	v_add_f32_e32 v116, 1.0, v116
	v_rcp_f32_e32 v116, v116
	s_ashr_i32 s41, s40, 31
	v_add_f32_e32 v112, 1.0, v112
	v_rcp_f32_e32 v112, v112
	v_mul_f32_e32 v116, v151, v116
	v_mul_f32_e32 v124, v150, v116
	v_mov_b32_e32 v116, v125
	v_pk_mul_f32 v[116:117], v[116:117], v[128:129] op_sel_hi:[1,0]
	v_mul_f32_e32 v120, v153, v112
	v_mul_f32_e32 v112, 0xbfb8aa3b, v117
	v_exp_f32_e32 v125, v112
	v_mov_b32_e32 v112, v121
	v_pk_mul_f32 v[112:113], v[112:113], v[128:129] op_sel_hi:[1,0]
	v_mul_f32_e32 v150, v152, v120
	v_mul_f32_e32 v121, 0xbfb8aa3b, v113
	v_exp_f32_e32 v121, v121
	v_add_f32_e32 v120, 1.0, v125
	v_rcp_f32_e32 v125, v120
	s_lshl_b64 s[40:41], s[40:41], 1
	v_add_f32_e32 v120, 1.0, v121
	v_rcp_f32_e32 v151, v120
	v_mov_b32_e32 v120, v126
	v_mov_b32_e32 v121, v118
	v_pk_mul_f32 v[120:121], v[120:121], v[128:129] op_sel_hi:[1,0]
	v_mul_f32_e32 v117, v117, v125
	v_mul_f32_e32 v118, 0xbfb8aa3b, v121
	v_exp_f32_e32 v118, v118
	v_mul_f32_e32 v125, v116, v117
	v_mov_b32_e32 v117, v114
	v_mul_f32_e32 v113, v113, v151
	v_add_f32_e32 v116, 1.0, v118
	v_rcp_f32_e32 v118, v116
	v_mov_b32_e32 v116, v122
	v_pk_mul_f32 v[116:117], v[116:117], v[128:129] op_sel_hi:[1,0]
	v_mul_f32_e32 v122, v112, v113
	v_mul_f32_e32 v114, 0xbfb8aa3b, v117
	v_exp_f32_e32 v114, v114
	v_mul_f32_e32 v112, v121, v118
	v_mul_f32_e32 v120, v120, v112
	v_mov_b32_e32 v118, v127
	v_add_f32_e32 v112, 1.0, v114
	v_rcp_f32_e32 v121, v112
	v_pk_mul_f32 v[112:113], v[118:119], v[128:129] op_sel_hi:[1,0]
	v_or_b32_e32 v145, 16, v148
	v_mul_f32_e32 v114, 0xbfb8aa3b, v113
	v_exp_f32_e32 v118, v114
	v_mov_b32_e32 v114, v123
	v_pk_mul_f32 v[114:115], v[114:115], v[128:129] op_sel_hi:[1,0]
	v_mul_f32_e32 v117, v117, v121
	v_mul_f32_e32 v119, 0xbfb8aa3b, v115
	v_exp_f32_e32 v119, v119
	v_add_f32_e32 v118, 1.0, v118
	v_rcp_f32_e32 v118, v118
	v_mul_f32_e32 v121, v116, v117
	v_add_f32_e32 v119, 1.0, v119
	v_rcp_f32_e32 v119, v119
	v_mul_f32_e32 v113, v113, v118
	v_mul_f32_e32 v112, v112, v113
	v_cvt_pk_bf16_f32 v117, v120, v112
	v_mul_f32_e32 v113, v115, v119
	v_mul_f32_e32 v113, v114, v113
	v_cvt_pk_bf16_f32 v119, v121, v113
	v_mov_b64_e32 v[112:113], s[66:67]
	v_mad_i64_i32 v[114:115], s[50:51], v148, s36, v[112:113]
	v_lshl_add_u64 v[114:115], v[114:115], 0, s[40:41]
	v_and_b32_e32 v128, 0xc0, v143
	v_lshl_add_u64 v[120:121], v[114:115], 0, v[128:129]
	v_and_b32_e32 v114, 48, v143
	v_mov_b32_e32 v115, v129
	v_lshl_add_u64 v[120:121], v[120:121], 0, v[114:115]
	v_or_b32_e32 v147, 32, v148
	v_or_b32_e32 v149, 48, v148
	v_add_u32_e32 v141, 0x80, v148
	v_add_u32_e32 v139, 0x90, v148
	v_add_u32_e32 v135, 0xa0, v148
	v_add_u32_e32 v131, 0xb0, v148
	v_cvt_pk_bf16_f32 v116, v124, v125
	v_cvt_pk_bf16_f32 v118, v150, v122
	global_store_dwordx4 v[120:121], v[116:119], off
	s_nop 1
	v_mov_b32_e32 v116, v108
	v_mov_b32_e32 v117, v100
	v_pk_mul_f32 v[116:117], v[116:117], v[146:147] op_sel_hi:[1,0]
	v_mov_b32_e32 v118, v104
	v_mul_f32_e32 v100, 0xbfb8aa3b, v117
	v_exp_f32_e32 v100, v100
	v_mov_b32_e32 v119, v96
	v_pk_mul_f32 v[118:119], v[118:119], v[146:147] op_sel_hi:[1,0]
	v_add_f32_e32 v100, 1.0, v100
	v_mul_f32_e32 v96, 0xbfb8aa3b, v119
	v_exp_f32_e32 v96, v96
	v_rcp_f32_e32 v100, v100
	v_add_f32_e32 v96, 1.0, v96
	v_rcp_f32_e32 v96, v96
	v_mul_f32_e32 v100, v117, v100
	v_mul_f32_e32 v108, v116, v100
	v_mov_b32_e32 v100, v109
	v_pk_mul_f32 v[100:101], v[100:101], v[146:147] op_sel_hi:[1,0]
	v_mul_f32_e32 v104, v119, v96
	v_mul_f32_e32 v96, 0xbfb8aa3b, v101
	v_exp_f32_e32 v109, v96
	v_mov_b32_e32 v96, v105
	v_pk_mul_f32 v[96:97], v[96:97], v[146:147] op_sel_hi:[1,0]
	v_mul_f32_e32 v116, v118, v104
	v_mul_f32_e32 v105, 0xbfb8aa3b, v97
	v_exp_f32_e32 v105, v105
	v_add_f32_e32 v104, 1.0, v109
	v_rcp_f32_e32 v109, v104
	v_add_f32_e32 v104, 1.0, v105
	v_rcp_f32_e32 v117, v104
	v_mov_b32_e32 v104, v110
	v_mov_b32_e32 v105, v102
	v_pk_mul_f32 v[104:105], v[104:105], v[146:147] op_sel_hi:[1,0]
	v_mul_f32_e32 v101, v101, v109
	v_mul_f32_e32 v102, 0xbfb8aa3b, v105
	v_exp_f32_e32 v102, v102
	v_mul_f32_e32 v109, v100, v101
	v_mov_b32_e32 v101, v98
	v_mul_f32_e32 v97, v97, v117
	v_add_f32_e32 v100, 1.0, v102
	v_rcp_f32_e32 v102, v100
	v_mov_b32_e32 v100, v106
	v_pk_mul_f32 v[100:101], v[100:101], v[146:147] op_sel_hi:[1,0]
	v_mul_f32_e32 v106, v96, v97
	v_mul_f32_e32 v98, 0xbfb8aa3b, v101
	v_exp_f32_e32 v98, v98
	v_mul_f32_e32 v96, v105, v102
	v_mul_f32_e32 v104, v104, v96
	v_mov_b32_e32 v102, v111
	v_add_f32_e32 v96, 1.0, v98
	v_rcp_f32_e32 v105, v96
	v_pk_mul_f32 v[96:97], v[102:103], v[146:147] op_sel_hi:[1,0]
	v_mul_f32_e32 v101, v101, v105
	v_mul_f32_e32 v98, 0xbfb8aa3b, v97
	v_exp_f32_e32 v102, v98
	v_mov_b32_e32 v98, v107
	v_pk_mul_f32 v[98:99], v[98:99], v[146:147] op_sel_hi:[1,0]
	v_mul_f32_e32 v100, v100, v101
	v_mul_f32_e32 v103, 0xbfb8aa3b, v99
	v_exp_f32_e32 v103, v103
	v_add_f32_e32 v102, 1.0, v102
	v_rcp_f32_e32 v102, v102
	v_add_f32_e32 v103, 1.0, v103
	v_rcp_f32_e32 v103, v103
	v_mul_f32_e32 v97, v97, v102
	v_mul_f32_e32 v97, v96, v97
	v_cvt_pk_bf16_f32 v97, v104, v97
	v_mul_f32_e32 v96, v99, v103
	v_mul_f32_e32 v99, v98, v96
	v_cvt_pk_bf16_f32 v99, v100, v99
	v_mad_i64_i32 v[100:101], s[50:51], v145, s36, v[112:113]
	v_lshl_add_u64 v[100:101], v[100:101], 0, s[40:41]
	v_lshl_add_u64 v[100:101], v[100:101], 0, v[128:129]
	v_lshl_add_u64 v[100:101], v[100:101], 0, v[114:115]
	v_cvt_pk_bf16_f32 v96, v108, v109
	v_cvt_pk_bf16_f32 v98, v116, v106
	global_store_dwordx4 v[100:101], v[96:99], off
	s_nop 1
	v_mov_b32_e32 v96, v92
	v_mov_b32_e32 v97, v84
	v_pk_mul_f32 v[96:97], v[96:97], v[144:145] op_sel_hi:[1,0]
	v_mov_b32_e32 v98, v88
	v_mul_f32_e32 v84, 0xbfb8aa3b, v97
	v_exp_f32_e32 v84, v84
	v_mov_b32_e32 v99, v80
	v_pk_mul_f32 v[98:99], v[98:99], v[144:145] op_sel_hi:[1,0]
	v_add_f32_e32 v84, 1.0, v84
	v_mul_f32_e32 v80, 0xbfb8aa3b, v99
	v_exp_f32_e32 v80, v80
	v_rcp_f32_e32 v84, v84
	v_add_f32_e32 v80, 1.0, v80
	v_rcp_f32_e32 v80, v80
	v_mul_f32_e32 v84, v97, v84
	v_mul_f32_e32 v92, v96, v84
	v_mov_b32_e32 v84, v93
	v_pk_mul_f32 v[84:85], v[84:85], v[144:145] op_sel_hi:[1,0]
	v_mul_f32_e32 v88, v99, v80
	v_mul_f32_e32 v80, 0xbfb8aa3b, v85
	v_exp_f32_e32 v93, v80
	v_mov_b32_e32 v80, v89
	v_pk_mul_f32 v[80:81], v[80:81], v[144:145] op_sel_hi:[1,0]
	v_mul_f32_e32 v96, v98, v88
	v_mul_f32_e32 v89, 0xbfb8aa3b, v81
	v_exp_f32_e32 v89, v89
	v_add_f32_e32 v88, 1.0, v93
	v_rcp_f32_e32 v93, v88
	v_add_f32_e32 v88, 1.0, v89
	v_rcp_f32_e32 v97, v88
	v_mov_b32_e32 v88, v94
	v_mov_b32_e32 v89, v86
	v_pk_mul_f32 v[88:89], v[88:89], v[144:145] op_sel_hi:[1,0]
	v_mul_f32_e32 v85, v85, v93
	v_mul_f32_e32 v86, 0xbfb8aa3b, v89
	v_exp_f32_e32 v86, v86
	v_mul_f32_e32 v93, v84, v85
	v_mov_b32_e32 v85, v82
	v_mul_f32_e32 v81, v81, v97
	v_add_f32_e32 v84, 1.0, v86
	v_rcp_f32_e32 v86, v84
	v_mov_b32_e32 v84, v90
	v_pk_mul_f32 v[84:85], v[84:85], v[144:145] op_sel_hi:[1,0]
	v_mul_f32_e32 v90, v80, v81
	v_mul_f32_e32 v82, 0xbfb8aa3b, v85
	v_exp_f32_e32 v82, v82
	v_mul_f32_e32 v80, v89, v86
	v_mul_f32_e32 v88, v88, v80
	v_mov_b32_e32 v86, v95
	v_add_f32_e32 v80, 1.0, v82
	v_rcp_f32_e32 v89, v80
	v_pk_mul_f32 v[80:81], v[86:87], v[144:145] op_sel_hi:[1,0]
	v_mul_f32_e32 v85, v85, v89
	v_mul_f32_e32 v82, 0xbfb8aa3b, v81
	v_exp_f32_e32 v86, v82
	v_mov_b32_e32 v82, v91
	v_pk_mul_f32 v[82:83], v[82:83], v[144:145] op_sel_hi:[1,0]
	v_mul_f32_e32 v84, v84, v85
	v_mul_f32_e32 v87, 0xbfb8aa3b, v83
	v_exp_f32_e32 v87, v87
	v_add_f32_e32 v86, 1.0, v86
	v_rcp_f32_e32 v86, v86
	v_add_f32_e32 v87, 1.0, v87
	v_rcp_f32_e32 v87, v87
	v_mul_f32_e32 v81, v81, v86
	v_mul_f32_e32 v81, v80, v81
	v_cvt_pk_bf16_f32 v81, v88, v81
	v_mul_f32_e32 v80, v83, v87
	v_mul_f32_e32 v83, v82, v80
	v_cvt_pk_bf16_f32 v83, v84, v83
	v_mad_i64_i32 v[84:85], s[50:51], v147, s36, v[112:113]
	v_lshl_add_u64 v[84:85], v[84:85], 0, s[40:41]
	v_lshl_add_u64 v[84:85], v[84:85], 0, v[128:129]
	v_lshl_add_u64 v[84:85], v[84:85], 0, v[114:115]
	v_cvt_pk_bf16_f32 v80, v92, v93
	v_cvt_pk_bf16_f32 v82, v96, v90
	global_store_dwordx4 v[84:85], v[80:83], off
	s_nop 1
	v_mov_b32_e32 v80, v76
	v_mov_b32_e32 v81, v68
	v_pk_mul_f32 v[80:81], v[80:81], v[142:143] op_sel_hi:[1,0]
	v_mov_b32_e32 v82, v72
	v_mul_f32_e32 v68, 0xbfb8aa3b, v81
	v_exp_f32_e32 v68, v68
	v_mov_b32_e32 v83, v64
	v_pk_mul_f32 v[82:83], v[82:83], v[142:143] op_sel_hi:[1,0]
	v_add_f32_e32 v68, 1.0, v68
	v_mul_f32_e32 v64, 0xbfb8aa3b, v83
	v_exp_f32_e32 v64, v64
	v_rcp_f32_e32 v68, v68
	v_add_f32_e32 v64, 1.0, v64
	v_rcp_f32_e32 v64, v64
	v_mul_f32_e32 v68, v81, v68
	v_mul_f32_e32 v76, v80, v68
	v_mov_b32_e32 v68, v77
	v_pk_mul_f32 v[68:69], v[68:69], v[142:143] op_sel_hi:[1,0]
	v_mul_f32_e32 v72, v83, v64
	v_mul_f32_e32 v64, 0xbfb8aa3b, v69
	v_exp_f32_e32 v77, v64
	v_mov_b32_e32 v64, v73
	v_pk_mul_f32 v[64:65], v[64:65], v[142:143] op_sel_hi:[1,0]
	v_mul_f32_e32 v80, v82, v72
	v_mul_f32_e32 v73, 0xbfb8aa3b, v65
	v_exp_f32_e32 v73, v73
	v_add_f32_e32 v72, 1.0, v77
	v_rcp_f32_e32 v77, v72
	v_add_f32_e32 v72, 1.0, v73
	v_rcp_f32_e32 v81, v72
	v_mov_b32_e32 v72, v78
	v_mov_b32_e32 v73, v70
	v_pk_mul_f32 v[72:73], v[72:73], v[142:143] op_sel_hi:[1,0]
	v_mul_f32_e32 v69, v69, v77
	v_mul_f32_e32 v70, 0xbfb8aa3b, v73
	v_exp_f32_e32 v70, v70
	v_mul_f32_e32 v77, v68, v69
	v_mov_b32_e32 v69, v66
	v_mul_f32_e32 v65, v65, v81
	v_add_f32_e32 v68, 1.0, v70
	v_rcp_f32_e32 v70, v68
	v_mov_b32_e32 v68, v74
	v_pk_mul_f32 v[68:69], v[68:69], v[142:143] op_sel_hi:[1,0]
	v_mul_f32_e32 v74, v64, v65
	v_mul_f32_e32 v66, 0xbfb8aa3b, v69
	v_exp_f32_e32 v66, v66
	v_mul_f32_e32 v64, v73, v70
	v_mul_f32_e32 v72, v72, v64
	v_mov_b32_e32 v70, v79
	v_add_f32_e32 v64, 1.0, v66
	v_rcp_f32_e32 v73, v64
	v_pk_mul_f32 v[64:65], v[70:71], v[142:143] op_sel_hi:[1,0]
	v_mul_f32_e32 v69, v69, v73
	v_mul_f32_e32 v66, 0xbfb8aa3b, v65
	v_exp_f32_e32 v70, v66
	v_mov_b32_e32 v66, v75
	v_pk_mul_f32 v[66:67], v[66:67], v[142:143] op_sel_hi:[1,0]
	v_mul_f32_e32 v68, v68, v69
	v_mul_f32_e32 v71, 0xbfb8aa3b, v67
	v_exp_f32_e32 v71, v71
	v_add_f32_e32 v70, 1.0, v70
	v_rcp_f32_e32 v70, v70
	v_add_f32_e32 v71, 1.0, v71
	v_rcp_f32_e32 v71, v71
	v_mul_f32_e32 v65, v65, v70
	v_mul_f32_e32 v65, v64, v65
	v_cvt_pk_bf16_f32 v65, v72, v65
	v_mul_f32_e32 v64, v67, v71
	v_mul_f32_e32 v67, v66, v64
	v_cvt_pk_bf16_f32 v67, v68, v67
	v_mad_i64_i32 v[68:69], s[50:51], v149, s36, v[112:113]
	v_lshl_add_u64 v[68:69], v[68:69], 0, s[40:41]
	v_lshl_add_u64 v[68:69], v[68:69], 0, v[128:129]
	v_lshl_add_u64 v[68:69], v[68:69], 0, v[114:115]
	v_cvt_pk_bf16_f32 v64, v76, v77
	v_cvt_pk_bf16_f32 v66, v80, v74
	global_store_dwordx4 v[68:69], v[64:67], off
	s_nop 1
	v_mov_b32_e32 v64, v60
	v_mov_b32_e32 v65, v52
	v_pk_mul_f32 v[64:65], v[64:65], v[140:141] op_sel_hi:[1,0]
	v_mov_b32_e32 v66, v56
	v_mul_f32_e32 v52, 0xbfb8aa3b, v65
	v_exp_f32_e32 v52, v52
	v_mov_b32_e32 v67, v48
	v_pk_mul_f32 v[66:67], v[66:67], v[140:141] op_sel_hi:[1,0]
	v_add_f32_e32 v52, 1.0, v52
	v_mul_f32_e32 v48, 0xbfb8aa3b, v67
	v_exp_f32_e32 v48, v48
	v_rcp_f32_e32 v52, v52
	v_add_f32_e32 v48, 1.0, v48
	v_rcp_f32_e32 v48, v48
	v_mul_f32_e32 v52, v65, v52
	v_mul_f32_e32 v60, v64, v52
	v_mov_b32_e32 v52, v61
	v_pk_mul_f32 v[52:53], v[52:53], v[140:141] op_sel_hi:[1,0]
	v_mul_f32_e32 v56, v67, v48
	v_mul_f32_e32 v48, 0xbfb8aa3b, v53
	v_exp_f32_e32 v61, v48
	v_mov_b32_e32 v48, v57
	v_pk_mul_f32 v[48:49], v[48:49], v[140:141] op_sel_hi:[1,0]
	v_mul_f32_e32 v64, v66, v56
	v_mul_f32_e32 v57, 0xbfb8aa3b, v49
	v_exp_f32_e32 v57, v57
	v_add_f32_e32 v56, 1.0, v61
	v_rcp_f32_e32 v61, v56
	v_add_f32_e32 v56, 1.0, v57
	v_rcp_f32_e32 v65, v56
	v_mov_b32_e32 v56, v62
	v_mov_b32_e32 v57, v54
	v_pk_mul_f32 v[56:57], v[56:57], v[140:141] op_sel_hi:[1,0]
	v_mul_f32_e32 v53, v53, v61
	v_mul_f32_e32 v54, 0xbfb8aa3b, v57
	v_exp_f32_e32 v54, v54
	v_mul_f32_e32 v61, v52, v53
	v_mov_b32_e32 v53, v50
	v_mul_f32_e32 v49, v49, v65
	v_add_f32_e32 v52, 1.0, v54
	v_rcp_f32_e32 v54, v52
	v_mov_b32_e32 v52, v58
	v_pk_mul_f32 v[52:53], v[52:53], v[140:141] op_sel_hi:[1,0]
	v_mul_f32_e32 v58, v48, v49
	v_mul_f32_e32 v50, 0xbfb8aa3b, v53
	v_exp_f32_e32 v50, v50
	v_mul_f32_e32 v48, v57, v54
	v_mul_f32_e32 v56, v56, v48
	v_mov_b32_e32 v54, v63
	v_add_f32_e32 v48, 1.0, v50
	v_rcp_f32_e32 v57, v48
	v_pk_mul_f32 v[48:49], v[54:55], v[140:141] op_sel_hi:[1,0]
	v_mul_f32_e32 v53, v53, v57
	v_mul_f32_e32 v50, 0xbfb8aa3b, v49
	v_exp_f32_e32 v54, v50
	v_mov_b32_e32 v50, v59
	v_pk_mul_f32 v[50:51], v[50:51], v[140:141] op_sel_hi:[1,0]
	v_mul_f32_e32 v52, v52, v53
	v_mul_f32_e32 v55, 0xbfb8aa3b, v51
	v_exp_f32_e32 v55, v55
	v_add_f32_e32 v54, 1.0, v54
	v_rcp_f32_e32 v54, v54
	v_add_f32_e32 v55, 1.0, v55
	v_rcp_f32_e32 v55, v55
	v_mul_f32_e32 v49, v49, v54
	v_mul_f32_e32 v49, v48, v49
	v_cvt_pk_bf16_f32 v49, v56, v49
	v_mul_f32_e32 v48, v51, v55
	v_mul_f32_e32 v51, v50, v48
	v_cvt_pk_bf16_f32 v51, v52, v51
	v_mad_i64_i32 v[52:53], s[50:51], v141, s36, v[112:113]
	v_lshl_add_u64 v[52:53], v[52:53], 0, s[40:41]
	v_lshl_add_u64 v[52:53], v[52:53], 0, v[128:129]
	v_lshl_add_u64 v[52:53], v[52:53], 0, v[114:115]
	v_cvt_pk_bf16_f32 v48, v60, v61
	v_cvt_pk_bf16_f32 v50, v64, v58
	global_store_dwordx4 v[52:53], v[48:51], off
	s_nop 1
	v_mov_b32_e32 v48, v44
	v_mov_b32_e32 v49, v36
	v_pk_mul_f32 v[48:49], v[48:49], v[138:139] op_sel_hi:[1,0]
	v_mov_b32_e32 v50, v40
	v_mul_f32_e32 v36, 0xbfb8aa3b, v49
	v_exp_f32_e32 v36, v36
	v_mov_b32_e32 v51, v32
	v_pk_mul_f32 v[50:51], v[50:51], v[138:139] op_sel_hi:[1,0]
	v_add_f32_e32 v36, 1.0, v36
	v_mul_f32_e32 v32, 0xbfb8aa3b, v51
	v_exp_f32_e32 v32, v32
	v_rcp_f32_e32 v36, v36
	v_add_f32_e32 v32, 1.0, v32
	v_rcp_f32_e32 v32, v32
	v_mul_f32_e32 v36, v49, v36
	v_mul_f32_e32 v44, v48, v36
	v_mov_b32_e32 v36, v45
	v_pk_mul_f32 v[36:37], v[36:37], v[138:139] op_sel_hi:[1,0]
	v_mul_f32_e32 v40, v51, v32
	v_mul_f32_e32 v32, 0xbfb8aa3b, v37
	v_exp_f32_e32 v45, v32
	v_mov_b32_e32 v32, v41
	v_pk_mul_f32 v[32:33], v[32:33], v[138:139] op_sel_hi:[1,0]
	v_mul_f32_e32 v48, v50, v40
	v_mul_f32_e32 v41, 0xbfb8aa3b, v33
	v_exp_f32_e32 v41, v41
	v_add_f32_e32 v40, 1.0, v45
	v_rcp_f32_e32 v45, v40
	v_add_f32_e32 v40, 1.0, v41
	v_rcp_f32_e32 v49, v40
	v_mov_b32_e32 v40, v46
	v_mov_b32_e32 v41, v38
	v_pk_mul_f32 v[40:41], v[40:41], v[138:139] op_sel_hi:[1,0]
	v_mul_f32_e32 v37, v37, v45
	v_mul_f32_e32 v38, 0xbfb8aa3b, v41
	v_exp_f32_e32 v38, v38
	v_mul_f32_e32 v45, v36, v37
	v_mov_b32_e32 v37, v34
	v_mul_f32_e32 v33, v33, v49
	v_add_f32_e32 v36, 1.0, v38
	v_rcp_f32_e32 v38, v36
	v_mov_b32_e32 v36, v42
	v_pk_mul_f32 v[36:37], v[36:37], v[138:139] op_sel_hi:[1,0]
	v_mul_f32_e32 v42, v32, v33
	v_mul_f32_e32 v34, 0xbfb8aa3b, v37
	v_exp_f32_e32 v34, v34
	v_mul_f32_e32 v32, v41, v38
	v_mul_f32_e32 v40, v40, v32
	v_mov_b32_e32 v38, v47
	v_add_f32_e32 v32, 1.0, v34
	v_rcp_f32_e32 v41, v32
	v_pk_mul_f32 v[32:33], v[38:39], v[138:139] op_sel_hi:[1,0]
	v_mul_f32_e32 v37, v37, v41
	v_mul_f32_e32 v34, 0xbfb8aa3b, v33
	v_exp_f32_e32 v38, v34
	v_mov_b32_e32 v34, v43
	v_pk_mul_f32 v[34:35], v[34:35], v[138:139] op_sel_hi:[1,0]
	v_mul_f32_e32 v36, v36, v37
	v_mul_f32_e32 v39, 0xbfb8aa3b, v35
	v_exp_f32_e32 v39, v39
	v_add_f32_e32 v38, 1.0, v38
	v_rcp_f32_e32 v38, v38
	v_add_f32_e32 v39, 1.0, v39
	v_rcp_f32_e32 v39, v39
	v_mul_f32_e32 v33, v33, v38
	v_mul_f32_e32 v33, v32, v33
	v_cvt_pk_bf16_f32 v33, v40, v33
	v_mul_f32_e32 v32, v35, v39
	v_mul_f32_e32 v35, v34, v32
	v_cvt_pk_bf16_f32 v35, v36, v35
	v_mad_i64_i32 v[36:37], s[50:51], v139, s36, v[112:113]
	v_lshl_add_u64 v[36:37], v[36:37], 0, s[40:41]
	v_lshl_add_u64 v[36:37], v[36:37], 0, v[128:129]
	v_lshl_add_u64 v[36:37], v[36:37], 0, v[114:115]
	v_cvt_pk_bf16_f32 v32, v44, v45
	v_cvt_pk_bf16_f32 v34, v48, v42
	global_store_dwordx4 v[36:37], v[32:35], off
	s_nop 1
	v_mov_b32_e32 v32, v28
	v_mov_b32_e32 v33, v20
	v_pk_mul_f32 v[32:33], v[32:33], v[134:135] op_sel_hi:[1,0]
	v_mov_b32_e32 v34, v24
	v_mul_f32_e32 v20, 0xbfb8aa3b, v33
	v_exp_f32_e32 v20, v20
	v_mov_b32_e32 v35, v16
	v_pk_mul_f32 v[34:35], v[34:35], v[134:135] op_sel_hi:[1,0]
	v_add_f32_e32 v20, 1.0, v20
	v_mul_f32_e32 v16, 0xbfb8aa3b, v35
	v_exp_f32_e32 v16, v16
	v_rcp_f32_e32 v20, v20
	v_add_f32_e32 v16, 1.0, v16
	v_rcp_f32_e32 v16, v16
	v_mul_f32_e32 v20, v33, v20
	v_mul_f32_e32 v28, v32, v20
	v_mov_b32_e32 v20, v29
	v_pk_mul_f32 v[20:21], v[20:21], v[134:135] op_sel_hi:[1,0]
	v_mul_f32_e32 v24, v35, v16
	v_mul_f32_e32 v16, 0xbfb8aa3b, v21
	v_exp_f32_e32 v29, v16
	v_mov_b32_e32 v16, v25
	v_pk_mul_f32 v[16:17], v[16:17], v[134:135] op_sel_hi:[1,0]
	v_mul_f32_e32 v32, v34, v24
	v_mul_f32_e32 v25, 0xbfb8aa3b, v17
	v_exp_f32_e32 v25, v25
	v_add_f32_e32 v24, 1.0, v29
	v_rcp_f32_e32 v29, v24
	v_add_f32_e32 v24, 1.0, v25
	v_rcp_f32_e32 v33, v24
	v_mov_b32_e32 v24, v30
	v_mov_b32_e32 v25, v22
	v_pk_mul_f32 v[24:25], v[24:25], v[134:135] op_sel_hi:[1,0]
	v_mul_f32_e32 v21, v21, v29
	v_mul_f32_e32 v22, 0xbfb8aa3b, v25
	v_exp_f32_e32 v22, v22
	v_mul_f32_e32 v29, v20, v21
	v_mov_b32_e32 v21, v18
	v_mul_f32_e32 v17, v17, v33
	v_add_f32_e32 v20, 1.0, v22
	v_rcp_f32_e32 v22, v20
	v_mov_b32_e32 v20, v26
	v_pk_mul_f32 v[20:21], v[20:21], v[134:135] op_sel_hi:[1,0]
	v_mul_f32_e32 v26, v16, v17
	v_mul_f32_e32 v18, 0xbfb8aa3b, v21
	v_exp_f32_e32 v18, v18
	v_mul_f32_e32 v16, v25, v22
	v_mul_f32_e32 v24, v24, v16
	v_mov_b32_e32 v22, v31
	v_add_f32_e32 v16, 1.0, v18
	v_rcp_f32_e32 v25, v16
	v_pk_mul_f32 v[16:17], v[22:23], v[134:135] op_sel_hi:[1,0]
	v_mul_f32_e32 v21, v21, v25
	v_mul_f32_e32 v18, 0xbfb8aa3b, v17
	v_exp_f32_e32 v22, v18
	v_mov_b32_e32 v18, v27
	v_pk_mul_f32 v[18:19], v[18:19], v[134:135] op_sel_hi:[1,0]
	v_mul_f32_e32 v20, v20, v21
	v_mul_f32_e32 v23, 0xbfb8aa3b, v19
	v_exp_f32_e32 v23, v23
	v_add_f32_e32 v22, 1.0, v22
	v_rcp_f32_e32 v22, v22
	v_add_f32_e32 v23, 1.0, v23
	v_rcp_f32_e32 v23, v23
	v_mul_f32_e32 v17, v17, v22
	v_mul_f32_e32 v17, v16, v17
	v_cvt_pk_bf16_f32 v17, v24, v17
	v_mul_f32_e32 v16, v19, v23
	v_mul_f32_e32 v19, v18, v16
	v_cvt_pk_bf16_f32 v19, v20, v19
	v_mad_i64_i32 v[20:21], s[50:51], v135, s36, v[112:113]
	v_lshl_add_u64 v[20:21], v[20:21], 0, s[40:41]
	v_lshl_add_u64 v[20:21], v[20:21], 0, v[128:129]
	v_lshl_add_u64 v[20:21], v[20:21], 0, v[114:115]
	v_cvt_pk_bf16_f32 v16, v28, v29
	v_cvt_pk_bf16_f32 v18, v32, v26
	global_store_dwordx4 v[20:21], v[16:19], off
	s_nop 1
	v_mov_b32_e32 v16, v12
	v_mov_b32_e32 v17, v4
	v_pk_mul_f32 v[16:17], v[16:17], v[130:131] op_sel_hi:[1,0]
	v_mov_b32_e32 v18, v8
	v_mul_f32_e32 v4, 0xbfb8aa3b, v17
	v_exp_f32_e32 v4, v4
	v_mov_b32_e32 v19, v0
	v_pk_mul_f32 v[18:19], v[18:19], v[130:131] op_sel_hi:[1,0]
	v_add_f32_e32 v4, 1.0, v4
	v_mul_f32_e32 v0, 0xbfb8aa3b, v19
	v_exp_f32_e32 v0, v0
	v_rcp_f32_e32 v4, v4
	v_add_f32_e32 v0, 1.0, v0
	v_rcp_f32_e32 v0, v0
	v_mul_f32_e32 v4, v17, v4
	v_mul_f32_e32 v12, v16, v4
	v_mov_b32_e32 v4, v13
	v_pk_mul_f32 v[4:5], v[4:5], v[130:131] op_sel_hi:[1,0]
	v_mul_f32_e32 v8, v19, v0
	v_mul_f32_e32 v0, 0xbfb8aa3b, v5
	v_exp_f32_e32 v13, v0
	v_mov_b32_e32 v0, v9
	v_pk_mul_f32 v[0:1], v[0:1], v[130:131] op_sel_hi:[1,0]
	v_mul_f32_e32 v16, v18, v8
	v_mul_f32_e32 v9, 0xbfb8aa3b, v1
	v_exp_f32_e32 v9, v9
	v_add_f32_e32 v8, 1.0, v13
	v_rcp_f32_e32 v13, v8
	v_add_f32_e32 v8, 1.0, v9
	v_rcp_f32_e32 v17, v8
	v_mov_b32_e32 v8, v14
	v_mov_b32_e32 v9, v6
	v_pk_mul_f32 v[8:9], v[8:9], v[130:131] op_sel_hi:[1,0]
	v_mul_f32_e32 v5, v5, v13
	v_mul_f32_e32 v6, 0xbfb8aa3b, v9
	v_exp_f32_e32 v6, v6
	v_mul_f32_e32 v13, v4, v5
	v_mov_b32_e32 v5, v2
	v_mul_f32_e32 v1, v1, v17
	v_add_f32_e32 v4, 1.0, v6
	v_rcp_f32_e32 v6, v4
	v_mov_b32_e32 v4, v10
	v_pk_mul_f32 v[4:5], v[4:5], v[130:131] op_sel_hi:[1,0]
	v_mul_f32_e32 v10, v0, v1
	v_mul_f32_e32 v2, 0xbfb8aa3b, v5
	v_exp_f32_e32 v2, v2
	v_mul_f32_e32 v0, v9, v6
	v_mul_f32_e32 v8, v8, v0
	v_mov_b32_e32 v6, v15
	v_add_f32_e32 v0, 1.0, v2
	v_rcp_f32_e32 v9, v0
	v_pk_mul_f32 v[0:1], v[6:7], v[130:131] op_sel_hi:[1,0]
	v_mul_f32_e32 v5, v5, v9
	v_mul_f32_e32 v2, 0xbfb8aa3b, v1
	v_exp_f32_e32 v6, v2
	v_mov_b32_e32 v2, v11
	v_pk_mul_f32 v[2:3], v[2:3], v[130:131] op_sel_hi:[1,0]
	v_mul_f32_e32 v4, v4, v5
	v_mul_f32_e32 v7, 0xbfb8aa3b, v3
	v_exp_f32_e32 v7, v7
	v_add_f32_e32 v6, 1.0, v6
	v_rcp_f32_e32 v6, v6
	v_add_f32_e32 v7, 1.0, v7
	v_rcp_f32_e32 v7, v7
	v_mul_f32_e32 v1, v1, v6
	v_mul_f32_e32 v1, v0, v1
	v_cvt_pk_bf16_f32 v1, v8, v1
	v_mul_f32_e32 v0, v3, v7
	v_mul_f32_e32 v3, v2, v0
	v_cvt_pk_bf16_f32 v3, v4, v3
	v_mad_i64_i32 v[4:5], s[50:51], v131, s36, v[112:113]
	v_lshl_add_u64 v[4:5], v[4:5], 0, s[40:41]
	v_lshl_add_u64 v[4:5], v[4:5], 0, v[128:129]
	v_lshl_add_u64 v[4:5], v[4:5], 0, v[114:115]
	v_cvt_pk_bf16_f32 v0, v12, v13
	v_cvt_pk_bf16_f32 v2, v16, v10
	global_store_dwordx4 v[4:5], v[0:3], off
	s_mov_b64 s[40:41], 0

.LBB0_1326:
	v_bfe_i32 v4, v0, 27, 1
	v_lshlrev_b32_e32 v1, 4, v0
	v_lshrrev_b32_e32 v4, 22, v4
	v_add_u32_e32 v4, v1, v4
	v_and_b32_e32 v4, 0xfffffc00, v4
	v_sub_u32_e32 v4, v1, v4
	v_lshrrev_b32_e32 v5, 4, v4
	v_bitop3_b32 v4, v5, v4, 32 bitop3:0x6c
	v_ashrrev_i32_e32 v6, 31, v4
	v_ashrrev_i32_e32 v2, 31, v0
	v_lshrrev_b32_e32 v6, 26, v6
	v_lshrrev_b32_e32 v2, 26, v2
	v_add_u32_e32 v6, v4, v6
	v_add_u32_e32 v2, v0, v2
	v_ashrrev_i32_e32 v7, 6, v6
	v_and_b32_e32 v6, 0xc0, v6
	v_ashrrev_i32_e32 v3, 6, v2
	v_sub_u32_e32 v4, v4, v6
	v_lshlrev_b32_e32 v5, 3, v3
	v_lshlrev_b32_e32 v8, 5, v3
	v_ashrrev_i16_sdwa v4, v133, sext(v4) dst_sel:DWORD dst_unused:UNUSED_PAD src0_sel:DWORD src1_sel:BYTE_0
	v_and_b32_e32 v5, 0x1ffff0, v5
	v_and_b32_e32 v8, 32, v8
	v_bfe_i32 v4, v4, 0, 16
	v_add_u32_e32 v6, v8, v4
	v_add_lshl_u32 v5, v7, v5, 11
	v_add_u32_e32 v1, 0x2000, v1
	v_lshl_add_u32 v128, v6, 1, v5
	v_ashrrev_i32_e32 v5, 31, v1
	v_lshrrev_b32_e32 v5, 22, v5
	v_add_u32_e32 v5, v1, v5
	v_ashrrev_i32_e32 v5, 10, v5
	v_mul_i32_i24_e32 v6, 0x400, v5
	v_sub_u32_e32 v1, v1, v6
	v_lshrrev_b32_e32 v6, 4, v1
	v_bitop3_b32 v1, v6, v1, 32 bitop3:0x6c
	v_ashrrev_i32_e32 v8, 31, v1
	v_lshrrev_b32_e32 v8, 26, v8
	v_add_u32_e32 v8, v1, v8
	v_ashrrev_i32_e32 v9, 6, v8
	v_and_b32_e32 v8, 0xc0, v8
	v_sub_u32_e32 v1, v1, v8
	v_lshlrev_b32_e32 v6, 3, v5
	v_lshlrev_b32_e32 v10, 5, v5
	v_ashrrev_i16_sdwa v1, v133, sext(v1) dst_sel:DWORD dst_unused:UNUSED_PAD src0_sel:DWORD src1_sel:BYTE_0
	v_and_b32_e32 v6, 0x1ffff0, v6
	v_and_b32_e32 v10, 32, v10
	v_bfe_i32 v8, v1, 0, 16
	v_add_u32_e32 v1, v10, v8
	v_add_lshl_u32 v6, v9, v6, 11
	v_lshl_add_u32 v130, v1, 1, v6
	v_and_b32_e32 v1, 15, v0
	s_ashr_i32 s33, s27, 6
	v_and_b32_e32 v6, 48, v0
	v_lshlrev_b32_e32 v1, 6, v1
	v_lshlrev_b32_e32 v0, 2, v0
	v_or_b32_e32 v10, v1, v6
	v_and_b32_e32 v0, 32, v0
	s_lshl_b32 s41, s33, 12
	s_lshl_b32 s40, s40, 13
	v_bitop3_b32 v1, v1, v0, v6 bitop3:0x36
	s_lshl_b32 s33, s33, 10
	v_bitop3_b32 v6, v10, s40, v0 bitop3:0xde
	s_and_b32 s40, s41, 0x3000
	v_or_b32_e32 v145, s40, v1
	s_add_i32 s40, s33, 0
	v_lshl_add_u64 v[0:1], s[34:35], 0, v[128:129]
	s_add_i32 m0, s40, 0x18000
	v_lshl_add_u64 v[0:1], v[0:1], 0, s[0:1]
	v_mov_b32_e32 v131, v129
	s_waitcnt vmcnt(16)
	s_barrier
	global_load_lds_dwordx4 v[0:1], off
	v_lshl_add_u64 v[0:1], s[34:35], 0, v[130:131]
	v_lshl_add_u64 v[0:1], v[0:1], 0, s[0:1]
	s_add_i32 m0, s40, 0x1a000
	s_add_i32 s41, s40, 0x8000
	global_load_lds_dwordx4 v[0:1], off
	v_lshl_add_u64 v[0:1], s[28:29], 0, v[128:129]
	v_lshl_add_u64 v[0:1], v[0:1], 0, s[0:1]
	s_mov_b32 m0, s41
	s_add_i32 s47, s40, 0xa000
	global_load_lds_dwordx4 v[0:1], off
	v_lshl_add_u64 v[0:1], s[28:29], 0, v[130:131]
	v_lshl_add_u64 v[0:1], v[0:1], 0, s[0:1]
	s_mov_b32 m0, s47
	s_add_u32 s34, s34, 0x40080
	global_load_lds_dwordx4 v[0:1], off
	s_addc_u32 s35, s35, 0
	s_add_i32 m0, s40, 0x1c000
	v_lshlrev_b32_e32 v0, 14, v3
	global_load_lds_dwordx4 v128, s[34:35]
	s_add_i32 m0, s40, 0x1e000
	v_and_b32_e32 v0, 0xffff8000, v0
	global_load_lds_dwordx4 v130, s[34:35]
	s_sub_i32 s34, s37, s46
	s_sub_i32 s34, s34, s21
	s_ashr_i32 s35, s34, 31
	s_lshl_b64 s[34:35], s[34:35], 19
	v_lshl_add_u32 v0, v7, 11, v0
	v_readlane_b32 s68, v254, 4
	v_and_or_b32 v0, v2, 64, v0
	s_add_u32 s34, s64, s34
	v_lshlrev_b32_e32 v2, 14, v5
	v_readlane_b32 s70, v254, 6
	v_readlane_b32 s71, v254, 7
	s_addc_u32 s35, s65, s35
	v_and_b32_e32 v2, 0xffff8000, v2
	s_mov_b64 s[50:51], s[70:71]
	v_lshl_add_u32 v2, v9, 11, v2
	v_lshlrev_b32_e32 v3, 6, v5
	s_add_u32 s30, s50, s30
	s_waitcnt vmcnt(22)
	v_lshl_add_u32 v0, v4, 1, v0
	v_mov_b32_e32 v1, v129
	v_and_or_b32 v2, v3, 64, v2
	s_addc_u32 s31, s51, s31
	v_lshl_add_u64 v[134:135], s[34:35], 0, v[0:1]
	v_lshl_add_u32 v2, v8, 1, v2
	v_mov_b32_e32 v3, v129
	v_lshl_add_u64 v[140:141], s[30:31], 0, v[0:1]
	v_mov_b32_e32 v0, 0
	v_lshl_add_u64 v[138:139], s[34:35], 0, v[2:3]
	v_lshl_add_u64 v[142:143], s[30:31], 0, v[2:3]
	s_mov_b32 s21, -2
	s_mov_b64 s[30:31], 0
	v_add_u32_e32 v144, 0, v6
	v_mov_b32_e32 v1, v0
	v_mov_b32_e32 v2, v0
	v_mov_b32_e32 v3, v0
	v_mov_b32_e32 v4, v0
	v_mov_b32_e32 v5, v0
	v_mov_b32_e32 v6, v0
	v_mov_b32_e32 v7, v0
	v_mov_b32_e32 v8, v0
	v_mov_b32_e32 v9, v0
	v_mov_b32_e32 v10, v0
	v_mov_b32_e32 v11, v0
	v_mov_b32_e32 v12, v0
	v_mov_b32_e32 v13, v0
	v_mov_b32_e32 v14, v0
	v_mov_b32_e32 v15, v0
	v_mov_b32_e32 v16, v0
	v_mov_b32_e32 v17, v0
	v_mov_b32_e32 v18, v0
	v_mov_b32_e32 v19, v0
	v_mov_b32_e32 v20, v0
	v_mov_b32_e32 v21, v0
	v_mov_b32_e32 v22, v0
	v_mov_b32_e32 v23, v0
	v_mov_b32_e32 v24, v0
	v_mov_b32_e32 v25, v0
	v_mov_b32_e32 v26, v0
	v_mov_b32_e32 v27, v0
	v_mov_b32_e32 v28, v0
	v_mov_b32_e32 v29, v0
	v_mov_b32_e32 v30, v0
	v_mov_b32_e32 v31, v0
	v_mov_b32_e32 v32, v0
	v_mov_b32_e32 v33, v0
	v_mov_b32_e32 v34, v0
	v_mov_b32_e32 v35, v0
	v_mov_b32_e32 v36, v0
	v_mov_b32_e32 v37, v0
	v_mov_b32_e32 v38, v0
	v_mov_b32_e32 v39, v0
	v_mov_b32_e32 v40, v0
	v_mov_b32_e32 v41, v0
	v_mov_b32_e32 v42, v0
	v_mov_b32_e32 v43, v0
	v_mov_b32_e32 v44, v0
	v_mov_b32_e32 v45, v0
	v_mov_b32_e32 v46, v0
	v_mov_b32_e32 v47, v0
	v_mov_b32_e32 v48, v0
	v_mov_b32_e32 v49, v0
	v_mov_b32_e32 v50, v0
	v_mov_b32_e32 v51, v0
	v_mov_b32_e32 v52, v0
	v_mov_b32_e32 v53, v0
	v_mov_b32_e32 v54, v0
	v_mov_b32_e32 v55, v0
	v_mov_b32_e32 v56, v0
	v_mov_b32_e32 v57, v0
	v_mov_b32_e32 v58, v0
	v_mov_b32_e32 v59, v0
	v_mov_b32_e32 v60, v0
	v_mov_b32_e32 v61, v0
	v_mov_b32_e32 v62, v0
	v_mov_b32_e32 v63, v0
	v_mov_b32_e32 v64, v0
	v_mov_b32_e32 v65, v0
	v_mov_b32_e32 v66, v0
	v_mov_b32_e32 v67, v0
	v_mov_b32_e32 v68, v0
	v_mov_b32_e32 v69, v0
	v_mov_b32_e32 v70, v0
	v_mov_b32_e32 v71, v0
	v_mov_b32_e32 v72, v0
	v_mov_b32_e32 v73, v0
	v_mov_b32_e32 v74, v0
	v_mov_b32_e32 v75, v0
	v_mov_b32_e32 v76, v0
	v_mov_b32_e32 v77, v0
	v_mov_b32_e32 v78, v0
	v_mov_b32_e32 v79, v0
	v_mov_b32_e32 v80, v0
	v_mov_b32_e32 v81, v0
	v_mov_b32_e32 v82, v0
	v_mov_b32_e32 v83, v0
	v_mov_b32_e32 v84, v0
	v_mov_b32_e32 v85, v0
	v_mov_b32_e32 v86, v0
	v_mov_b32_e32 v87, v0
	v_mov_b32_e32 v88, v0
	v_mov_b32_e32 v89, v0
	v_mov_b32_e32 v90, v0
	v_mov_b32_e32 v91, v0
	v_mov_b32_e32 v92, v0
	v_mov_b32_e32 v93, v0
	v_mov_b32_e32 v94, v0
	v_mov_b32_e32 v95, v0
	v_mov_b32_e32 v96, v0
	v_mov_b32_e32 v97, v0
	v_mov_b32_e32 v98, v0
	v_mov_b32_e32 v99, v0
	v_mov_b32_e32 v100, v0
	v_mov_b32_e32 v101, v0
	v_mov_b32_e32 v102, v0
	v_mov_b32_e32 v103, v0
	v_mov_b32_e32 v104, v0
	v_mov_b32_e32 v105, v0
	v_mov_b32_e32 v106, v0
	v_mov_b32_e32 v107, v0
	v_mov_b32_e32 v108, v0
	v_mov_b32_e32 v109, v0
	v_mov_b32_e32 v110, v0
	v_mov_b32_e32 v111, v0
	v_mov_b32_e32 v112, v0
	v_mov_b32_e32 v113, v0
	v_mov_b32_e32 v114, v0
	v_mov_b32_e32 v115, v0
	v_mov_b32_e32 v116, v0
	v_mov_b32_e32 v117, v0
	v_mov_b32_e32 v118, v0
	v_mov_b32_e32 v119, v0
	v_mov_b32_e32 v120, v0
	v_mov_b32_e32 v121, v0
	v_mov_b32_e32 v122, v0
	v_mov_b32_e32 v123, v0
	v_mov_b32_e32 v124, v0
	v_mov_b32_e32 v125, v0
	v_mov_b32_e32 v126, v0
	v_mov_b32_e32 v127, v0
	s_barrier
	v_readlane_b32 s69, v254, 5
	v_readlane_b32 s72, v254, 8
	v_readlane_b32 s73, v254, 9
	v_readlane_b32 s74, v254, 10
	v_readlane_b32 s75, v254, 11
	v_readlane_b32 s76, v254, 12
	v_readlane_b32 s77, v254, 13
	v_readlane_b32 s78, v254, 14
	v_readlane_b32 s79, v254, 15
	v_readlane_b32 s80, v254, 16
	v_readlane_b32 s81, v254, 17
	v_readlane_b32 s82, v254, 18
	v_readlane_b32 s83, v254, 19
